# split seams 4/5: first slot poll issued together with the arrival atomic (one round trip instead of two)
# speedup vs baseline: 1.0066x; 1.0066x over previous
.LBB0_782:
	s_mov_b32 s101, 0
	s_cmp_gt_i32 s69, 5
	s_cselect_b64 s[0:1], -1, 0
	s_and_b64 s[2:3], s[18:19], s[0:1]
	s_andn2_b64 vcc, exec, s[2:3]
	s_cbranch_vccnz .LBB0_836
	v_mov_b32_e32 v0, 0x20040
	ds_read_b32 v1, v0 offset:16
	ds_read_b32 v3, v0 offset:8
	s_waitcnt lgkmcnt(0)
	v_readfirstlane_b32 s6, v1
	s_nop 3
	s_cmp_eq_u32 s6, 0
	s_cbranch_scc1 .Ls4_orig
	s_waitcnt vmcnt(0)
	s_barrier
	v_cmp_gt_u32_e32 vcc, 64, v199
	s_cbranch_vccz .Ls4_done
	s_lshl_b32 s6, s33, 8
	s_add_u32 s6, s92, s6
	s_addc_u32 s7, s93, 0
	v_mov_b32_e32 v0, 0x1400
	v_mov_b32_e32 v1, 1
	s_lshl_b32 s10, s33, 7
	s_add_u32 s10, s10, 0x3a00
	v_lshl_add_u32 v4, v199, 2, s10
	v_lshl_add_u32 v3, v3, 2, s10
	v_cmp_eq_u32_e32 vcc, 0, v199
	s_and_saveexec_b64 s[12:13], vcc
	global_store_dword v3, v1, s[92:93]
	global_atomic_add v2, v0, v1, s[6:7] sc0
	s_mov_b64 exec, s[12:13]
	global_load_dword v5, v4, s[92:93] sc1
	s_waitcnt vmcnt(0)
	v_readfirstlane_b32 s11, v2
	s_nop 3
	s_lshr_b32 s101, s11, 5
	s_add_i32 s101, s101, 1
	s_and_b32 s11, s11, 31
	s_cmp_eq_u32 s11, 31
	s_cbranch_scc0 .Ls4_wait
	buffer_wbl2 sc1
	s_waitcnt vmcnt(0)
	v_mov_b32_e32 v0, 0xfc03000
	s_and_saveexec_b64 s[12:13], vcc
	global_atomic_add v2, v0, v1, s[30:31] offset:1024 sc0
	s_mov_b64 exec, s[12:13]
	s_waitcnt vmcnt(0)
	v_readfirstlane_b32 s11, v2
	s_nop 3
	s_and_b32 s11, s11, 7
	s_cmp_eq_u32 s11, 7
	s_cbranch_scc0 .Ls4_wait
	v_mov_b32_e32 v0, 0xfc03500
	s_and_saveexec_b64 s[12:13], vcc
	global_atomic_add v0, v1, s[30:31]
	s_mov_b64 exec, s[12:13]
.Ls4_wait:
	v_cmp_gt_u32_e32 vcc, 32, v199
	s_and_saveexec_b64 s[12:13], vcc
	s_mov_b32 s14, 0x8000
	s_branch .Ls4_check

.Ls4_check:
	v_cmp_gt_u32_e32 vcc, 1, v5
	s_cbranch_vccz .Ls4_got
	s_sleep 1
	s_sub_u32 s14, s14, 1
	s_cmp_lg_u32 s14, 0
	s_cbranch_scc1 .Ls4_poll

.Lp5_tail:
	s_cmp_gt_i32 s69, 6
	s_cselect_b64 s[0:1], -1, 0
	s_and_b64 s[2:3], s[4:5], s[0:1]
	s_andn2_b64 vcc, exec, s[2:3]
	s_cbranch_vccnz .LBB0_1453
	s_cmp_eq_u32 s98, 2
	s_cbranch_scc0 .Lsb_orig
	s_waitcnt vmcnt(0) lgkmcnt(0)
	s_barrier
	s_mov_b32 s98, 3
	v_cmp_gt_u32_e32 vcc, 64, v199
	s_cbranch_vccz .Lsb_done
	s_lshl_b32 s6, s33, 8
	s_add_u32 s6, s92, s6
	s_addc_u32 s7, s93, 0
	v_mov_b32_e32 v0, 0x1400
	v_mov_b32_e32 v1, 1
	s_lshl_b32 s10, s33, 7
	s_add_u32 s10, s10, 0x3600
	v_lshl_add_u32 v4, v199, 2, s10
	v_cmp_eq_u32_e32 vcc, 0, v199
	s_and_saveexec_b64 s[12:13], vcc
	global_atomic_add v2, v0, v1, s[6:7] sc0
	s_mov_b64 exec, s[12:13]
	global_load_dword v5, v4, s[92:93] sc1
	s_waitcnt vmcnt(0)
	v_readfirstlane_b32 s11, v2
	s_nop 3
	s_lshr_b32 s99, s11, 5
	s_and_b32 s11, s11, 31
	s_cmp_eq_u32 s11, 31
	s_cbranch_scc0 .Lsb_waitA
	buffer_wbl2 sc1
	s_waitcnt vmcnt(0)
	v_mov_b32_e32 v0, 0xfc03000
	s_and_saveexec_b64 s[12:13], vcc
	global_atomic_add v2, v0, v1, s[30:31] offset:1024 sc0
	s_mov_b64 exec, s[12:13]
	s_waitcnt vmcnt(0)
	v_readfirstlane_b32 s11, v2
	s_nop 3
	s_and_b32 s11, s11, 7
	s_cmp_eq_u32 s11, 7
	s_cbranch_scc0 .Lsb_waitA
	v_mov_b32_e32 v0, 0xfc03500
	s_and_saveexec_b64 s[12:13], vcc
	global_atomic_add v0, v1, s[30:31]
	s_mov_b64 exec, s[12:13]

.Lsb_checkA:
	v_cmp_gt_u32_e32 vcc, 7, v5
	s_cbranch_vccz .Lsb_gotA
	s_sleep 1
	s_sub_u32 s14, s14, 1
	s_cmp_lg_u32 s14, 0
	s_cbranch_scc1 .Lsb_pollA
